# grid barrier: waiters poll top-level generation directly, per-XCD generation hop removed
# speedup vs baseline: 1.0159x; 1.0078x over previous
.LBB0_892:
	s_or_b64 exec, exec, s[8:9]
	v_cvt_f32_u32_e32 v6, v4
	s_waitcnt vmcnt(0)
	v_readfirstlane_b32 s2, v5
	v_sub_u32_e32 v5, 0, v4
	v_rcp_iflag_f32_e32 v6, v6
	v_add_u32_e32 v7, s2, v1
	v_mul_f32_e32 v6, 0x4f7ffffe, v6
	v_cvt_u32_f32_e32 v6, v6
	v_mul_lo_u32 v1, v5, v6
	v_mul_hi_u32 v1, v6, v1
	v_add_u32_e32 v1, v6, v1
	v_mul_hi_u32 v1, v7, v1
	v_mul_lo_u32 v5, v1, v4
	v_sub_u32_e32 v5, v7, v5
	v_add_u32_e32 v6, 1, v1
	v_cmp_ge_u32_e32 vcc, v5, v4
	s_nop 1
	v_cndmask_b32_e32 v1, v1, v6, vcc
	v_sub_u32_e32 v6, v5, v4
	v_cndmask_b32_e32 v5, v5, v6, vcc
	v_add_u32_e32 v6, 1, v1
	v_cmp_ge_u32_e32 vcc, v5, v4
	v_add_u32_e32 v5, 1, v7
	s_nop 0
	v_cndmask_b32_e32 v1, v1, v6, vcc
	v_mul_lo_u32 v6, v4, v1
	v_add_u32_e32 v4, v6, v4
	v_cmp_ne_u32_e32 vcc, v5, v4
	s_and_saveexec_b64 s[2:3], vcc
	s_xor_b64 s[6:7], exec, s[2:3]
	s_cbranch_execz .LBB0_906
	s_waitcnt lgkmcnt(0)
	s_add_u32 s12, s28, 0x13ca3500
	s_addc_u32 s13, s29, 0
	global_load_dword v2, v3, s[12:13] sc1
	s_waitcnt vmcnt(0)
	v_cmp_eq_u32_e32 vcc, v2, v1
	s_and_saveexec_b64 s[8:9], vcc
	s_cbranch_execz .LBB0_905
	s_add_u32 s10, s28, 0x13ca0200
	s_addc_u32 s11, s29, 0
	s_mov_b32 s2, 1
	s_mov_b64 s[14:15], 0
	s_branch .LBB0_896

.LBB0_924:
	s_getpc_b64 s[98:99]
